# v102 + weight-transpose loops: loop-top waits no longer include the previous tile's store (vmcnt 2/1), first tile waited in the preheader
# baseline (speedup 1.0000x reference)
.LBB0_302:
	s_or_b64 exec, exec, s[28:29]
	v_readlane_b32 s0, v253, 29
	v_readlane_b32 s1, v253, 30
	v_mov_b32_e32 v0, v179
	s_andn2_b64 vcc, exec, s[0:1]
	s_waitcnt vmcnt(0) lgkmcnt(0)
	s_barrier
	s_cbranch_vccnz .LBB0_321
	v_ashrrev_i32_e32 v23, 4, v0
	v_readlane_b32 s0, v253, 44
	v_lshlrev_b32_e32 v1, 2, v0
	v_and_b32_e32 v4, 60, v1
	v_add_u32_e32 v2, s0, v23
	v_ashrrev_i32_e32 v3, 31, v2
	v_readlane_b32 s0, v253, 45
	v_lshlrev_b64 v[2:3], 13, v[2:3]
	v_readlane_b32 s1, v253, 46
	v_lshlrev_b32_e32 v176, 2, v4
	v_ashrrev_i32_e32 v31, 3, v0
	v_lshl_add_u64 v[2:3], s[0:1], 0, v[2:3]
	v_lshl_add_u64 v[2:3], v[2:3], 0, v[176:177]
	v_add_co_u32_e32 v6, vcc, 0x40000, v2
	s_movk_i32 s0, 0x104
	s_nop 0
	v_addc_co_u32_e32 v7, vcc, 0, v3, vcc
	global_load_dwordx4 v[8:11], v[2:3], off
	global_load_dwordx4 v[12:15], v[6:7], off
	v_lshlrev_b32_e32 v0, 3, v0
	v_mul_lo_u32 v1, v23, s0
	v_and_b32_e32 v0, 56, v0
	v_add3_u32 v30, 0, v1, v176
	v_lshl_add_u32 v1, v31, 2, 0
	v_xor_b32_e32 v32, 32, v31
	v_mul_u32_u24_e32 v2, 0x104, v0
	v_cmp_lt_i32_e64 s[38:39], 32, v31
	v_mad_u32_u24 v33, v0, s0, 0
	v_lshlrev_b32_e32 v34, 1, v32
	v_lshlrev_b32_e32 v35, 1, v31
	v_lshlrev_b32_e32 v16, 2, v4
	v_add_u32_e32 v36, v1, v2
	v_lshlrev_b32_e32 v176, 1, v0
	s_mov_b32 s3, s96
	s_waitcnt vmcnt(0)
	s_branch .LBB0_306

.LBB0_306:
	s_nop 0
	v_add_u32_e32 v0, 0x2080, v30
	s_barrier
	s_waitcnt vmcnt(2)
	ds_write2_b32 v30, v8, v9 offset1:1
	ds_write2_b32 v30, v10, v11 offset0:2 offset1:3
	s_waitcnt vmcnt(1)
	ds_write2_b32 v0, v12, v13 offset1:1
	v_add_u32_e32 v0, 0x2088, v30
	ds_write2_b32 v0, v14, v15 offset1:1
	s_waitcnt lgkmcnt(0)
	s_barrier
	s_load_dword s0, s[74:75], 0x0
	s_waitcnt lgkmcnt(0)
	s_add_i32 s2, s3, s0
	s_cmpk_gt_i32 s2, 0x1ff
	s_cselect_b64 s[0:1], -1, 0
	s_and_b64 vcc, exec, s[0:1]
	s_cbranch_vccnz .LBB0_309
	s_ashr_i32 s6, s2, 31
	s_lshr_b32 s6, s6, 28
	s_add_i32 s6, s2, s6
	s_and_b32 s7, s6, 0x3fffff0
	s_sub_i32 s7, s2, s7
	v_lshl_add_u32 v0, s7, 6, v23
	s_lshl_b32 s6, s6, 2
	v_ashrrev_i32_e32 v1, 31, v0
	v_readlane_b32 s56, v252, 10
	s_andn2_b32 s6, s6, 63
	v_lshlrev_b64 v[0:1], 13, v[0:1]
	v_readlane_b32 s60, v252, 14
	v_readlane_b32 s61, v252, 15
	s_ashr_i32 s7, s6, 31
	v_mov_b32_e32 v17, v177
	v_lshl_add_u64 v[0:1], s[60:61], 0, v[0:1]
	v_lshl_add_u64 v[0:1], s[6:7], 2, v[0:1]
	v_lshl_add_u64 v[0:1], v[0:1], 0, v[16:17]
	v_add_co_u32_e32 v2, vcc, 0x40000, v0
	v_readlane_b32 s62, v252, 16
	s_nop 0
	v_addc_co_u32_e32 v3, vcc, 0, v1, vcc
	global_load_dwordx4 v[8:11], v[0:1], off
	global_load_dwordx4 v[12:15], v[2:3], off
	v_readlane_b32 s63, v252, 17
	v_readlane_b32 s64, v252, 18
	v_readlane_b32 s65, v252, 19
	v_readlane_b32 s66, v252, 20
	v_readlane_b32 s67, v252, 21
	v_readlane_b32 s68, v252, 22
	v_readlane_b32 s69, v252, 23
	v_readlane_b32 s70, v252, 24
	v_readlane_b32 s71, v252, 25
	v_readlane_b32 s68, v255, 14
	v_readlane_b32 s70, v255, 12
	v_readlane_b32 s62, v255, 10
	v_readlane_b32 s64, v255, 6
	v_readlane_b32 s69, v255, 15
	v_readlane_b32 s71, v255, 13
	v_readlane_b32 s63, v255, 11
	v_readlane_b32 s65, v255, 7
	v_readlane_b32 s66, v255, 8
	v_readlane_b32 s67, v255, 9
	v_readlane_b32 s57, v252, 11
	v_readlane_b32 s58, v252, 12
	v_readlane_b32 s59, v252, 13
	s_cmpk_gt_i32 s3, 0x7f
	s_mov_b64 s[28:29], -1
	s_cbranch_scc1 .LBB0_310

.LBB0_321:
	v_readlane_b32 s0, v253, 47
	v_readlane_b32 s1, v253, 48
	v_mov_b32_e32 v0, v179
	s_andn2_b64 vcc, exec, s[0:1]
	v_cndmask_b32_e64 v1, 0, 1, s[0:1]
	v_cmp_ne_u32_e64 s[38:39], 1, v1
	s_cbranch_vccnz .LBB0_340
	v_ashrrev_i32_e32 v23, 4, v0
	v_readlane_b32 s0, v253, 44
	v_lshlrev_b32_e32 v1, 2, v0
	v_and_b32_e32 v4, 60, v1
	v_add_u32_e32 v2, s0, v23
	v_ashrrev_i32_e32 v3, 31, v2
	v_readlane_b32 s0, v253, 49
	v_lshlrev_b64 v[2:3], 12, v[2:3]
	v_readlane_b32 s1, v253, 50
	v_lshlrev_b32_e32 v176, 2, v4
	v_ashrrev_i32_e32 v31, 3, v0
	v_lshl_add_u64 v[2:3], s[0:1], 0, v[2:3]
	v_lshl_add_u64 v[2:3], v[2:3], 0, v[176:177]
	v_add_co_u32_e32 v6, vcc, 0x20000, v2
	s_movk_i32 s0, 0x104
	s_nop 0
	v_addc_co_u32_e32 v7, vcc, 0, v3, vcc
	global_load_dwordx4 v[8:11], v[2:3], off
	global_load_dwordx4 v[12:15], v[6:7], off
	v_lshlrev_b32_e32 v0, 3, v0
	v_mul_lo_u32 v1, v23, s0
	v_and_b32_e32 v0, 56, v0
	v_add3_u32 v30, 0, v1, v176
	v_lshl_add_u32 v1, v31, 2, 0
	v_xor_b32_e32 v32, 32, v31
	v_mul_u32_u24_e32 v2, 0x104, v0
	v_cmp_lt_i32_e64 s[40:41], 32, v31
	v_mad_u32_u24 v33, v0, s0, 0
	v_lshlrev_b32_e32 v34, 1, v32
	v_lshlrev_b32_e32 v35, 1, v31
	v_lshlrev_b32_e32 v16, 2, v4
	v_add_u32_e32 v36, v1, v2
	v_lshlrev_b32_e32 v176, 1, v0
	s_mov_b32 s3, s96
	s_waitcnt vmcnt(0)
	s_branch .LBB0_325

.LBB0_325:
	s_nop 0
	v_add_u32_e32 v0, 0x2080, v30
	s_barrier
	s_waitcnt vmcnt(2)
	ds_write2_b32 v30, v8, v9 offset1:1
	ds_write2_b32 v30, v10, v11 offset0:2 offset1:3
	s_waitcnt vmcnt(1)
	ds_write2_b32 v0, v12, v13 offset1:1
	v_add_u32_e32 v0, 0x2088, v30
	ds_write2_b32 v0, v14, v15 offset1:1
	s_waitcnt lgkmcnt(0)
	s_barrier
	s_load_dword s0, s[74:75], 0x0
	s_waitcnt lgkmcnt(0)
	s_add_i32 s2, s3, s0
	s_cmpk_gt_i32 s2, 0xff
	s_cselect_b64 s[0:1], -1, 0
	s_and_b64 vcc, exec, s[0:1]
	s_cbranch_vccnz .LBB0_328
	s_ashr_i32 s6, s2, 31
	s_lshr_b32 s6, s6, 28
	s_add_i32 s6, s2, s6
	s_and_b32 s7, s6, 0x3fffff0
	s_sub_i32 s7, s2, s7
	v_lshl_add_u32 v0, s7, 6, v23
	s_lshl_b32 s6, s6, 2
	v_ashrrev_i32_e32 v1, 31, v0
	s_andn2_b32 s6, s6, 63
	v_lshlrev_b64 v[0:1], 12, v[0:1]
	v_lshl_add_u64 v[0:1], s[88:89], 0, v[0:1]
	s_ashr_i32 s7, s6, 31
	v_lshl_add_u64 v[0:1], s[6:7], 2, v[0:1]
	v_mov_b32_e32 v17, v177
	v_lshl_add_u64 v[0:1], v[0:1], 0, v[16:17]
	v_add_co_u32_e32 v2, vcc, 0x20000, v0
	s_nop 1
	v_addc_co_u32_e32 v3, vcc, 0, v1, vcc
	global_load_dwordx4 v[8:11], v[0:1], off
	global_load_dwordx4 v[12:15], v[2:3], off
	s_cmp_gt_i32 s3, -16
	s_mov_b64 s[28:29], -1
	s_cbranch_scc1 .LBB0_329

.LBB0_340:
	v_readlane_b32 s0, v253, 42
	v_readlane_b32 s1, v253, 43
	v_mov_b32_e32 v0, v179
	s_andn2_b64 vcc, exec, s[0:1]
	v_cndmask_b32_e64 v1, 0, 1, s[0:1]
	v_cmp_ne_u32_e64 s[40:41], 1, v1
	s_cbranch_vccnz .LBB0_361
	v_ashrrev_i32_e32 v17, 4, v0
	v_readlane_b32 s0, v253, 44
	v_lshlrev_b32_e32 v1, 2, v0
	v_and_b32_e32 v4, 60, v1
	v_add_u32_e32 v2, s0, v17
	v_ashrrev_i32_e32 v3, 31, v2
	v_readlane_b32 s0, v253, 51
	v_lshlrev_b64 v[2:3], 14, v[2:3]
	v_readlane_b32 s1, v253, 52
	v_lshlrev_b32_e32 v176, 2, v4
	v_ashrrev_i32_e32 v32, 3, v0
	v_lshl_add_u64 v[2:3], s[0:1], 0, v[2:3]
	v_lshl_add_u64 v[2:3], v[2:3], 0, v[176:177]
	v_add_co_u32_e32 v6, vcc, 0x80000, v2
	s_movk_i32 s0, 0x104
	s_nop 0
	v_addc_co_u32_e32 v7, vcc, 0, v3, vcc
	global_load_dwordx4 v[8:11], v[2:3], off
	global_load_dwordx4 v[12:15], v[6:7], off
	v_lshlrev_b32_e32 v0, 3, v0
	v_mul_lo_u32 v1, v17, s0
	v_and_b32_e32 v16, 56, v0
	v_add3_u32 v25, 0, v1, v176
	v_lshl_add_u32 v0, v32, 2, 0
	v_xor_b32_e32 v33, 32, v32
	v_mul_u32_u24_e32 v1, 0x104, v16
	v_cmp_lt_i32_e64 s[42:43], 32, v32
	v_mad_u32_u24 v34, v16, s0, 0
	v_lshlrev_b32_e32 v35, 1, v33
	v_lshlrev_b32_e32 v36, 1, v32
	v_lshlrev_b32_e32 v18, 2, v4
	v_add_u32_e32 v37, v0, v1
	s_mov_b32 s3, s96
	s_waitcnt vmcnt(0)
	s_branch .LBB0_343

.LBB0_343:
	s_nop 0
	v_add_u32_e32 v0, 0x2080, v25
	s_barrier
	s_waitcnt vmcnt(2)
	ds_write2_b32 v25, v8, v9 offset1:1
	ds_write2_b32 v25, v10, v11 offset0:2 offset1:3
	s_waitcnt vmcnt(1)
	ds_write2_b32 v0, v12, v13 offset1:1
	v_add_u32_e32 v0, 0x2088, v25
	ds_write2_b32 v0, v14, v15 offset1:1
	s_waitcnt lgkmcnt(0)
	s_barrier
	s_load_dword s0, s[74:75], 0x0
	s_waitcnt lgkmcnt(0)
	s_add_i32 s2, s3, s0
	s_cmpk_gt_i32 s2, 0x3ff
	s_cselect_b64 s[0:1], -1, 0
	s_and_b64 vcc, exec, s[0:1]
	s_cbranch_vccnz .LBB0_346
	s_ashr_i32 s6, s2, 31
	s_lshr_b32 s6, s6, 28
	s_add_i32 s6, s2, s6
	s_and_b32 s7, s6, 0x3fffff0
	s_sub_i32 s7, s2, s7
	v_lshl_add_u32 v0, s7, 6, v17
	s_lshl_b32 s6, s6, 2
	v_ashrrev_i32_e32 v1, 31, v0
	v_readlane_b32 s44, v252, 0
	s_andn2_b32 s6, s6, 63
	v_lshlrev_b64 v[0:1], 14, v[0:1]
	v_readlane_b32 s45, v252, 1
	s_ashr_i32 s7, s6, 31
	v_mov_b32_e32 v19, v177
	v_lshl_add_u64 v[0:1], s[44:45], 0, v[0:1]
	v_lshl_add_u64 v[0:1], s[6:7], 2, v[0:1]
	v_lshl_add_u64 v[0:1], v[0:1], 0, v[18:19]
	v_add_co_u32_e32 v2, vcc, 0x80000, v0
	v_readlane_b32 s50, v252, 6
	s_nop 0
	v_addc_co_u32_e32 v3, vcc, 0, v1, vcc
	global_load_dwordx4 v[8:11], v[0:1], off
	global_load_dwordx4 v[12:15], v[2:3], off
	v_readlane_b32 s51, v252, 7
	v_readlane_b32 s50, v254, 13
	v_readlane_b32 s51, v254, 14
	v_readlane_b32 s46, v252, 2
	v_readlane_b32 s47, v252, 3
	v_readlane_b32 s48, v252, 4
	v_readlane_b32 s49, v252, 5
	s_cmp_gt_i32 s3, -16
	s_mov_b64 s[28:29], -1
	s_cbranch_scc1 .LBB0_347

.LBB0_361:
	s_nop 0
	v_mov_b32_e32 v0, v179
	s_and_b64 vcc, exec, s[40:41]
	s_cbranch_vccnz .LBB0_380
	v_ashrrev_i32_e32 v23, 4, v0
	v_readlane_b32 s0, v253, 55
	v_lshlrev_b32_e32 v1, 2, v0
	v_and_b32_e32 v4, 60, v1
	v_add_u32_e32 v2, s0, v23
	v_ashrrev_i32_e32 v3, 31, v2
	v_readlane_b32 s0, v253, 56
	v_lshlrev_b64 v[2:3], 12, v[2:3]
	v_readlane_b32 s1, v253, 57
	v_lshlrev_b32_e32 v176, 2, v4
	v_ashrrev_i32_e32 v31, 3, v0
	v_lshl_add_u64 v[2:3], s[0:1], 0, v[2:3]
	v_lshl_add_u64 v[2:3], v[2:3], 0, v[176:177]
	v_add_co_u32_e32 v6, vcc, 0x20000, v2
	s_movk_i32 s0, 0x104
	s_nop 0
	v_addc_co_u32_e32 v7, vcc, 0, v3, vcc
	global_load_dwordx4 v[8:11], v[2:3], off
	global_load_dwordx4 v[12:15], v[6:7], off
	v_lshlrev_b32_e32 v0, 3, v0
	v_mul_lo_u32 v1, v23, s0
	v_and_b32_e32 v0, 56, v0
	v_add3_u32 v30, 0, v1, v176
	v_lshl_add_u32 v1, v31, 2, 0
	v_xor_b32_e32 v32, 32, v31
	v_mul_u32_u24_e32 v2, 0x104, v0
	v_cmp_lt_i32_e64 s[40:41], 32, v31
	v_mad_u32_u24 v33, v0, s0, 0
	v_lshlrev_b32_e32 v34, 1, v32
	v_lshlrev_b32_e32 v35, 1, v31
	v_lshlrev_b32_e32 v16, 2, v4
	v_add_u32_e32 v36, v1, v2
	v_lshlrev_b32_e32 v176, 1, v0
	s_mov_b32 s3, s96
	s_waitcnt vmcnt(0)
	s_branch .LBB0_365

.LBB0_365:
	s_nop 0
	v_add_u32_e32 v0, 0x2080, v30
	s_barrier
	s_waitcnt vmcnt(2)
	ds_write2_b32 v30, v8, v9 offset1:1
	ds_write2_b32 v30, v10, v11 offset0:2 offset1:3
	s_waitcnt vmcnt(1)
	ds_write2_b32 v0, v12, v13 offset1:1
	v_add_u32_e32 v0, 0x2088, v30
	ds_write2_b32 v0, v14, v15 offset1:1
	s_waitcnt lgkmcnt(0)
	s_barrier
	s_load_dword s0, s[74:75], 0x0
	s_waitcnt lgkmcnt(0)
	s_add_i32 s2, s3, s0
	s_cmpk_gt_i32 s2, 0x3ff
	s_cselect_b64 s[0:1], -1, 0
	s_and_b64 vcc, exec, s[0:1]
	s_cbranch_vccnz .LBB0_368
	s_ashr_i32 s6, s2, 31
	s_lshr_b32 s6, s6, 26
	s_add_i32 s6, s2, s6
	s_andn2_b32 s6, s6, 63
	s_sub_i32 s7, s2, s6
	v_lshl_add_u32 v0, s7, 6, v23
	v_ashrrev_i32_e32 v1, 31, v0
	v_readlane_b32 s44, v252, 0
	v_lshlrev_b64 v[0:1], 12, v[0:1]
	v_readlane_b32 s46, v252, 2
	v_readlane_b32 s47, v252, 3
	s_ashr_i32 s7, s6, 31
	v_mov_b32_e32 v17, v177
	v_lshl_add_u64 v[0:1], s[46:47], 0, v[0:1]
	v_lshl_add_u64 v[0:1], s[6:7], 2, v[0:1]
	v_lshl_add_u64 v[0:1], v[0:1], 0, v[16:17]
	v_add_co_u32_e32 v2, vcc, 0x20000, v0
	v_readlane_b32 s50, v252, 6
	s_nop 0
	v_addc_co_u32_e32 v3, vcc, 0, v1, vcc
	global_load_dwordx4 v[8:11], v[0:1], off
	global_load_dwordx4 v[12:15], v[2:3], off
	v_readlane_b32 s51, v252, 7
	v_readlane_b32 s50, v254, 13
	v_readlane_b32 s51, v254, 14
	v_readlane_b32 s45, v252, 1
	v_readlane_b32 s48, v252, 4
	v_readlane_b32 s49, v252, 5
	s_cmpk_gt_i32 s3, 0xffc0
	s_mov_b64 s[28:29], -1
	s_cbranch_scc1 .LBB0_369
